# mixer job queue: first ticket of each workgroup per layer is its own id (no atomic burst at phase start); counter hands out tickets from 512
# speedup vs baseline: 1.0433x; 1.0101x over previous
.LBB0_369:
	s_or_b64 exec, exec, s[0:1]
	v_readlane_b32 s8, v252, 2
	v_readlane_b32 s9, v252, 3
	s_mov_b64 s[8:9], 0x3e38aa3b
	v_readlane_b32 s10, v252, 4
	v_readlane_b32 s11, v252, 5
	v_readlane_b32 s14, v252, 8
	v_readlane_b32 s15, v252, 9
	s_lshl_b32 s0, s34, 4
	s_mov_b32 s1, s9
	s_mov_b64 s[14:15], s[10:11]
	s_lshl_b64 s[0:1], s[0:1], 2
	s_waitcnt lgkmcnt(0)
	s_barrier
	s_add_u32 s0, s14, s0
	s_addc_u32 s1, s15, s1
	s_add_u32 s0, s0, 0xf213640
	s_addc_u32 s1, s1, 0
	s_mov_b32 s10, s34
	v_writelane_b32 v253, s0, 49
	s_mov_b32 s11, s9
	v_readlane_b32 s12, v252, 6
	v_writelane_b32 v253, s1, 50
	s_lshl_b64 s[0:1], s[10:11], 2
	s_add_u32 s2, s14, s0
	s_addc_u32 s3, s15, s1
	s_add_u32 s0, s2, 0xf2136c0
	s_addc_u32 s1, s3, 0
	v_writelane_b32 v253, s0, 51
	v_readlane_b32 s13, v252, 7
	v_mov_b32_e32 v234, v250
	v_writelane_b32 v253, s1, 52
	s_nop 0
	v_readlane_b32 s0, v253, 25
	v_readlane_b32 s1, v253, 26
	s_and_b64 s[0:1], s[0:1], exec
	s_cselect_b32 s1, 0x80, 0
	s_cselect_b32 s0, 0xffffff80, 0
	s_or_b32 s8, s1, 0xc00
	v_writelane_b32 v253, s8, 53
	s_or_b32 s8, s1, 0x400
	v_writelane_b32 v253, s8, 54
	s_or_b32 s8, s1, 0x600
	v_writelane_b32 v253, s8, 55
	s_add_i32 s8, s0, 0xfffffa00
	v_writelane_b32 v253, s8, 56
	s_addk_i32 s0, 0xfc00
	v_writelane_b32 v253, s0, 57
	s_lshl_b32 s8, s34, 1
	s_lshl_b32 s79, s1, 8
	v_writelane_b32 v253, s8, 58
	s_lshl_b32 s8, s34, 11
	s_add_u32 s2, s2, 0xf213600
	s_addc_u32 s3, s3, 0
	v_writelane_b32 v253, s2, 59
	s_mul_i32 s0, s34, 0x18000
	s_mov_b32 s1, s9
	v_writelane_b32 v253, s3, 60
	s_add_u32 s2, s14, 0xb1d0000
	s_addc_u32 s3, s15, 0
	v_writelane_b32 v253, s2, 61
	s_nop 1
	v_writelane_b32 v253, s3, 62
	s_add_u32 s2, s14, 0xc9d0000
	s_addc_u32 s3, s15, 0
	v_writelane_b32 v253, s2, 63
	s_nop 1
	v_writelane_b32 v254, s3, 0
	s_add_u32 s2, s14, 0xbdd0000
	s_addc_u32 s3, s15, 0
	v_writelane_b32 v254, s2, 1
	s_nop 1
	v_writelane_b32 v254, s3, 2
	s_add_u32 s2, s14, 0x3dd0000
	s_addc_u32 s3, s15, 0
	v_writelane_b32 v254, s2, 3
	s_nop 1
	v_writelane_b32 v254, s3, 4
	s_add_u32 s2, s14, 0xd1d0000
	v_writelane_b32 v254, s2, 5
	s_addc_u32 s2, s15, 0
	v_writelane_b32 v254, s2, 6
	s_add_u32 s2, s14, 0xd1f0000
	v_writelane_b32 v254, s2, 7
	s_addc_u32 s2, s15, 0
	v_writelane_b32 v254, s2, 8
	s_add_u32 s2, s14, 0xd210000
	s_addc_u32 s3, s15, 0
	v_writelane_b32 v254, s2, 9
	s_nop 1
	v_writelane_b32 v254, s3, 10
	s_add_u32 s2, s14, 0xf00000
	v_writelane_b32 v254, s2, 11
	s_addc_u32 s2, s15, 0
	s_add_u32 s94, s14, 0x780000
	s_addc_u32 s95, s15, 0
	v_writelane_b32 v254, s2, 12
	s_add_u32 s2, s14, 0x1330000
	s_addc_u32 s3, s15, 0
	v_writelane_b32 v254, s2, 13
	s_nop 1
	v_writelane_b32 v254, s3, 14
	s_add_u32 s2, s14, 0x1380000
	s_addc_u32 s3, s15, 0
	s_add_u32 s20, s14, 0x15a0000
	s_addc_u32 s21, s15, 0
	s_add_u32 s96, s14, 0x16a0000
	v_writelane_b32 v254, s2, 15
	s_addc_u32 s97, s15, 0
	s_nop 0
	v_writelane_b32 v254, s3, 16
	s_add_u32 s2, s14, 0x17b0000
	s_addc_u32 s3, s15, 0
	v_writelane_b32 v254, s2, 17
	s_nop 1
	v_writelane_b32 v254, s3, 18
	s_add_u32 s2, s14, 0x17b8000
	s_addc_u32 s3, s15, 0
	v_writelane_b32 v254, s2, 19
	s_add_u32 s12, s14, 0x1bc0000
	s_addc_u32 s13, s15, 0
	v_writelane_b32 v254, s3, 20
	v_writelane_b32 v254, s12, 21
	s_nop 1
	v_writelane_b32 v254, s13, 22
	s_add_u32 s12, s14, 0x1cc0000
	s_addc_u32 s13, s15, 0
	v_writelane_b32 v254, s12, 23
	s_nop 1
	v_writelane_b32 v254, s13, 24
	s_add_u32 s12, s14, 0x3dd0a00
	s_addc_u32 s13, s15, 0
	s_lshl_b32 s10, s34, 17
	v_writelane_b32 v254, s12, 25
	s_add_u32 s10, s14, s10
	s_addc_u32 s11, s15, 0
	v_writelane_b32 v254, s13, 26
	s_mov_b32 s12, s34
	v_writelane_b32 v254, s12, 27
	s_add_u32 s10, s10, 0x1360000
	s_addc_u32 s11, s11, 0
	v_writelane_b32 v254, s13, 28
	v_writelane_b32 v254, s10, 29
	s_nop 1
	v_writelane_b32 v254, s11, 30
	s_add_u32 s10, s14, 0x3dd0800
	s_addc_u32 s11, s15, 0
	s_lshl_b64 s[0:1], s[0:1], 1
	s_add_u32 s0, s14, s0
	s_addc_u32 s1, s15, s1
	v_writelane_b32 v254, s10, 31
	s_add_u32 s0, s0, 0x1300000
	s_addc_u32 s1, s1, 0
	v_writelane_b32 v254, s11, 32
	v_writelane_b32 v254, s0, 33
	s_nop 1
	v_writelane_b32 v254, s1, 34
	s_add_u32 s0, s14, 0x13a0000
	v_writelane_b32 v254, s0, 35
	s_addc_u32 s0, s15, 0
	v_writelane_b32 v254, s0, 36
	s_mov_b64 s[0:1], 0
	v_writelane_b32 v254, s0, 37
	s_nop 1
	v_writelane_b32 v254, s1, 38
	s_lshl_b64 s[0:1], s[8:9], 2
	v_writelane_b32 v254, s0, 39
	s_nop 1
	v_writelane_b32 v254, s1, 40
	s_mov_b64 s[0:1], 0
	v_writelane_b32 v254, s0, 41
	s_nop 1
	v_writelane_b32 v254, s1, 42
	v_writelane_b32 v254, s14, 43
	s_nop 1
	v_writelane_b32 v254, s15, 44
	v_readlane_b32 s0, v252, 8
	s_cmpk_eq_u32 s0, 0x200
	s_cselect_b32 s0, 1, 0
	s_nop 0
	v_writelane_b32 v255, s0, 41
	s_lshl_b32 s0, s0, 9
	s_nop 0
	v_writelane_b32 v255, s0, 42
	s_branch .LBB0_374

.Ljq_issued:
	s_or_b64 exec, exec, s[8:9]
	s_barrier
	s_and_saveexec_b64 s[8:9], s[0:1]
	s_cbranch_execz .LBB0_376
	s_waitcnt vmcnt(0) lgkmcnt(0)
	v_readlane_b32 s10, v255, 41
	s_cmp_lg_u32 s10, 0
	s_cbranch_scc1 .Ljq_first
	v_readlane_b32 s10, v255, 42
	s_nop 0
	v_add_u32_e32 v0, s10, v0
	s_branch .Ljq_got
.Ljq_first:
	v_writelane_b32 v255, 0, 41
	v_readlane_b32 s10, v253, 27
	s_nop 0
	v_mov_b32_e32 v0, s10
